# speedup vs baseline: 1.0090x; 1.0031x over previous
; DI unsigned cvtpk(float lo, float hi) { f32x2_t v = {lo, hi}; bf16x2_t b = __builtin_convertvector(v, bf16x2_t); return __builtin_bit_cast(unsigned, b); }
; __global__ void __launch_bounds__(NTHR, 2) mega_fwd(Params P) {
;     ...
; #pragma unroll
;                 for (int o = 1; o < 64; o <<= 1)
; #pragma unroll
;                     for (int k = 0; k < 2; ++k) { sk[k] += __shfl_xor(sk[k], o); sq[k] += __shfl_xor(sq[k], o); }
; #pragma unroll
;                 for (int k = 0; k < 2; ++k) {
;                     if (k == 1 && !has1) break;
;                     const int m = mm[k]; const int pos = pos_of_row(m); const size_t kvr = (size_t)kvrow_of_row(m);
;                     float* ockv; float* okr;
;                     if (m < MP) { ockv = outp + O_CKVP + ((size_t)ll * MP + m) * 256; okr = outp + O_KRP + ((size_t)ll * MP + m) * 32; }
;                     else { ockv = outp + O_CKVS + ((size_t)ll * MS + (m - MP)) * 256; okr = outp + O_KRS + ((size_t)ll * MS + (m - MP)) * 32; }
;                     {
;                         const float rs = 1.f / sqrtf(sk[k] * (1.f / 256.f) + EPS);
;                         const f32x4 o = vk[k] * rs * ((const f32x4*)gkv)[lane];
;                         ((f32x4*)ockv)[lane] = o;
;                         u32x2 w; w.x = cvtpk(o.x, o.y); w.y = cvtpk(o.z, o.w); ((u32x2*)(CKVB + kvr * 256))[lane] = w;
;                     }
;                     {
;                         const float rs = 1.f / sqrtf(sq[k] * (1.f / 384.f) + EPS);
;                         const f32x4 o0 = vq0[k] * rs * ((const f32x4*)gq)[lane];
;                         u32x2 w; w.x = cvtpk(o0.x, o0.y); w.y = cvtpk(o0.z, o0.w); ((u32x2*)(CQ + (size_t)m * 384))[lane] = w;
;                         if (lane < 32) { const f32x4 o1 = vq1[k] * rs * ((const f32x4*)(gq + 256))[lane]; u32x2 w1; w1.x = cvtpk(o1.x, o1.y); w1.y = cvtpk(o1.z, o1.w); ((u32x2*)(CQ + (size_t)m * 384 + 256))[lane] = w1; }
;                     }
;                     if (lane < 16) {
;                         const float2 cs = tabM[(size_t)pos * 16 + lane];
.LBB0_547:
	s_or_b64 exec, exec, s[46:47]
	s_waitcnt vmcnt(3)
	v_mul_f32_e32 v33, v23, v23
	v_mul_f32_e32 v57, v25, v25
	v_fmac_f32_e32 v33, v22, v22
	v_fmac_f32_e32 v57, v24, v24
	v_add_f32_e32 v33, v33, v57
	s_waitcnt vmcnt(2)
	v_mul_f32_e32 v57, v19, v19
	v_mul_f32_e32 v59, v21, v21
	v_fmac_f32_e32 v57, v18, v18
	v_fmac_f32_e32 v59, v20, v20
	v_add_f32_e32 v57, v57, v59
	v_mul_f32_e32 v59, v15, v15
	v_fmac_f32_e32 v59, v14, v14
	v_add_f32_e32 v57, v59, v57
	v_mul_f32_e32 v59, v17, v17
	v_fmac_f32_e32 v59, v16, v16
	v_add_f32_e32 v57, v59, v57
	s_waitcnt vmcnt(1)
	v_mul_f32_e32 v59, v11, v11
	v_mul_f32_e32 v65, v13, v13
	v_fmac_f32_e32 v59, v10, v10
	v_fmac_f32_e32 v65, v12, v12
	v_add_f32_e32 v59, v59, v65
	s_waitcnt vmcnt(0)
	v_mul_f32_e32 v65, v7, v7
	s_waitcnt lgkmcnt(1)
	v_mul_f32_e32 v67, v9, v9
	v_fmac_f32_e32 v65, v6, v6
	v_fmac_f32_e32 v67, v8, v8
	v_add_f32_e32 v65, v65, v67
	v_mul_f32_e32 v67, v3, v3
	v_fmac_f32_e32 v67, v2, v2
	v_add_f32_e32 v65, v67, v65
	v_mul_f32_e32 v67, v5, v5
	v_fmac_f32_e32 v67, v4, v4
	v_add_f32_e32 v65, v67, v65
	ds_bpermute_b32 v67, v29, v33
	ds_bpermute_b32 v68, v29, v57
	ds_bpermute_b32 v69, v29, v59
	ds_bpermute_b32 v70, v29, v65
	s_mov_b32 s4, 0x8000
	s_waitcnt lgkmcnt(3)
	v_add_f32_e32 v33, v33, v67
	s_waitcnt lgkmcnt(2)
	v_add_f32_e32 v57, v57, v68
	s_waitcnt lgkmcnt(1)
	v_add_f32_e32 v59, v59, v69
	s_waitcnt lgkmcnt(0)
	v_add_f32_e32 v65, v65, v70
	ds_bpermute_b32 v67, v76, v33
	ds_bpermute_b32 v68, v76, v57
	ds_bpermute_b32 v69, v76, v59
	ds_bpermute_b32 v70, v76, v65
	v_cmp_gt_i32_e64 s[46:47], s4, v26
	v_cmp_gt_i32_e64 s[100:101], s4, v58
	v_and_b32_e32 v116, 0x1fff, v26
	v_and_b32_e32 v117, 63, v26
	v_or_b32_e32 v117, 0x1000, v117
	v_cndmask_b32_e64 v116, v117, v116, s[46:47]
	v_lshl_or_b32 v116, v116, 7, v32
	global_load_dwordx2 v[116:117], v116, s[56:57]
	v_and_b32_e32 v118, 0x1fff, v58
	v_and_b32_e32 v119, 63, v58
	v_or_b32_e32 v119, 0x1000, v119
	v_cndmask_b32_e64 v118, v119, v118, s[100:101]
	v_lshl_or_b32 v118, v118, 7, v32
	global_load_dwordx2 v[118:119], v118, s[56:57]
	s_waitcnt lgkmcnt(3)
	v_add_f32_e32 v33, v33, v67
	s_waitcnt lgkmcnt(2)
	v_add_f32_e32 v57, v57, v68
	s_waitcnt lgkmcnt(1)
	v_add_f32_e32 v59, v59, v69
	s_waitcnt lgkmcnt(0)
	v_add_f32_e32 v65, v65, v70
	ds_bpermute_b32 v67, v77, v33
	ds_bpermute_b32 v68, v77, v57
	ds_bpermute_b32 v69, v77, v59
	ds_bpermute_b32 v70, v77, v65
	v_cmp_lt_i32_e32 vcc, s9, v26
	s_waitcnt lgkmcnt(3)
	v_add_f32_e32 v33, v33, v67
	s_waitcnt lgkmcnt(2)
	v_add_f32_e32 v57, v57, v68
	s_waitcnt lgkmcnt(1)
	v_add_f32_e32 v59, v59, v69
	s_waitcnt lgkmcnt(0)
	v_add_f32_e32 v65, v65, v70
	ds_bpermute_b32 v67, v78, v33
	ds_bpermute_b32 v68, v78, v57
	ds_bpermute_b32 v69, v78, v59
	ds_bpermute_b32 v70, v78, v65
	v_add_u32_e32 v72, 0xffff8000, v26
	s_waitcnt lgkmcnt(3)
	v_add_f32_e32 v33, v33, v67
	s_waitcnt lgkmcnt(2)
	v_add_f32_e32 v57, v57, v68
	s_waitcnt lgkmcnt(1)
	v_add_f32_e32 v59, v59, v69
	s_waitcnt lgkmcnt(0)
	v_add_f32_e32 v67, v65, v70
	ds_bpermute_b32 v65, v79, v33
	ds_bpermute_b32 v68, v79, v57
	ds_bpermute_b32 v69, v79, v59
	ds_bpermute_b32 v70, v79, v67
	s_waitcnt lgkmcnt(3)
	v_add_f32_e32 v65, v33, v65
	s_waitcnt lgkmcnt(2)
	v_add_f32_e32 v82, v57, v68
	s_waitcnt lgkmcnt(1)
	v_add_f32_e32 v33, v59, v69
	s_waitcnt lgkmcnt(0)
	v_add_f32_e32 v57, v67, v70
	ds_bpermute_b32 v83, v80, v65
	ds_bpermute_b32 v84, v80, v82
	ds_bpermute_b32 v67, v80, v33
	ds_bpermute_b32 v81, v80, v57
	v_and_b32_e32 v59, 63, v26
	v_mov_b64_e32 v[68:69], v[26:27]
	s_and_saveexec_b64 s[48:49], vcc
	v_lshrrev_b32_e32 v68, 6, v72
	s_movk_i32 s4, 0x1040
	v_mul_lo_u32 v68, v68, s4
	v_or_b32_e32 v68, v68, v59
	v_add_u32_e32 v68, 0x9000, v68
	v_mov_b32_e32 v69, v0
	s_or_b64 exec, exec, s[48:49]
	s_and_saveexec_b64 s[4:5], vcc
	s_xor_b64 s[48:49], exec, s[4:5]
	v_mov_b32_e32 v73, v0
	v_lshl_add_u64 v[70:71], s[58:59], 0, v[72:73]
	s_or_saveexec_b64 s[48:49], s[48:49]
	v_mov_b64_e32 v[72:73], 0xd000000
	v_mov_b64_e32 v[74:75], 0xcf00000
	s_xor_b64 exec, exec, s[48:49]
	v_lshl_add_u64 v[70:71], s[60:61], 0, v[26:27]
	v_mov_b64_e32 v[72:73], 0xc200000
	v_mov_b64_e32 v[74:75], 0x8200000
	s_or_b64 exec, exec, s[48:49]
	s_waitcnt lgkmcnt(3)
; DI unsigned cvtpk(float lo, float hi) { f32x2_t v = {lo, hi}; bf16x2_t b = __builtin_convertvector(v, bf16x2_t); return __builtin_bit_cast(unsigned, b); }
; __global__ void __launch_bounds__(NTHR, 2) mega_fwd(Params P) {
;     ...
;                     {
;                         const float rs = 1.f / sqrtf(sk[k] * (1.f / 256.f) + EPS);
;                         const f32x4 o = vk[k] * rs * ((const f32x4*)gkv)[lane];
;                         ((f32x4*)ockv)[lane] = o;
;                         u32x2 w; w.x = cvtpk(o.x, o.y); w.y = cvtpk(o.z, o.w); ((u32x2*)(CKVB + kvr * 256))[lane] = w;
;                     }
;                     {
;                         const float rs = 1.f / sqrtf(sq[k] * (1.f / 384.f) + EPS);
;                         const f32x4 o0 = vq0[k] * rs * ((const f32x4*)gq)[lane];
;                         u32x2 w; w.x = cvtpk(o0.x, o0.y); w.y = cvtpk(o0.z, o0.w); ((u32x2*)(CQ + (size_t)m * 384))[lane] = w;
;                         if (lane < 32) { const f32x4 o1 = vq1[k] * rs * ((const f32x4*)(gq + 256))[lane]; u32x2 w1; w1.x = cvtpk(o1.x, o1.y); w1.y = cvtpk(o1.z, o1.w); ((u32x2*)(CQ + (size_t)m * 384 + 256))[lane] = w1; }
;                     }
	v_add_f32_e32 v65, v65, v83
	s_waitcnt lgkmcnt(2)
	v_add_f32_e32 v86, v82, v84
	v_lshl_add_u64 v[74:75], s[52:53], 0, v[74:75]
	v_lshlrev_b64 v[82:83], 10, v[70:71]
	v_fmamk_f32 v65, v65, 0x3b800000, v214
	s_mov_b32 s6, 0xf800000
	v_lshl_add_u64 v[74:75], v[74:75], 0, v[82:83]
	v_cmp_gt_f32_e32 vcc, s6, v65
	v_mul_f32_e32 v82, 0x4f800000, v65
	s_nop 0
	v_cndmask_b32_e32 v65, v65, v82, vcc
	v_sqrt_f32_e32 v82, v65
	s_nop 0
	v_add_u32_e32 v83, -1, v82
	v_fma_f32 v84, -v83, v82, v65
	v_cmp_ge_f32_e64 s[48:49], 0, v84
	v_add_u32_e32 v84, 1, v82
	s_nop 0
	v_cndmask_b32_e64 v83, v82, v83, s[48:49]
	v_fma_f32 v82, -v84, v82, v65
	v_cmp_lt_f32_e64 s[48:49], 0, v82
	s_nop 1
	v_cndmask_b32_e64 v82, v83, v84, s[48:49]
	v_mul_f32_e32 v83, 0x37800000, v82
	v_cndmask_b32_e32 v82, v82, v83, vcc
	v_cmp_class_f32_e32 vcc, v65, v215
	s_nop 1
	v_cndmask_b32_e32 v65, v82, v65, vcc
	v_div_scale_f32 v82, s[4:5], v65, v65, 1.0
	v_rcp_f32_e32 v83, v82
	s_nop 0
	v_fma_f32 v84, -v82, v83, 1.0
	v_fmac_f32_e32 v83, v84, v83
	v_div_scale_f32 v84, vcc, 1.0, v65, 1.0
	v_mul_f32_e32 v85, v84, v83
	v_fma_f32 v87, -v82, v85, v84
	v_fmac_f32_e32 v85, v87, v83
	v_fma_f32 v82, -v82, v85, v84
	v_div_fmas_f32 v82, v82, v83, v85
	v_div_fixup_f32 v82, v82, v65, 1.0
	v_pk_mul_f32 v[84:85], v[22:23], v[82:83] op_sel_hi:[1,0]
	v_pk_mul_f32 v[82:83], v[24:25], v[82:83] op_sel_hi:[1,0]
	v_mov_b32_e32 v65, v0
	v_lshl_add_u64 v[74:75], v[74:75], 0, v[64:65]
	s_waitcnt vmcnt(0)
	v_pk_mul_f32 v[24:25], v[82:83], v[102:103]
	v_pk_mul_f32 v[22:23], v[84:85], v[100:101]
	global_store_dwordx4 v[74:75], v[22:25], off nt
	s_nop 1
	v_cvt_pk_bf16_f32 v22, v22, v23
	v_cvt_pk_bf16_f32 v23, v24, v25
	v_lshlrev_b64 v[24:25], 9, v[68:69]
	v_lshl_add_u64 v[24:25], v[34:35], 0, v[24:25]
	global_store_dwordx2 v[24:25], v[22:23], off
	v_fmamk_f32 v22, v86, 0x3b2aaaab, v214
	v_cmp_gt_f32_e32 vcc, s6, v22
	v_mul_f32_e32 v23, 0x4f800000, v22
	s_nop 0
	v_cndmask_b32_e32 v22, v22, v23, vcc
	v_sqrt_f32_e32 v23, v22
	s_nop 0
	v_add_u32_e32 v24, -1, v23
	v_fma_f32 v25, -v24, v23, v22
	v_cmp_ge_f32_e64 s[48:49], 0, v25
	v_add_u32_e32 v25, 1, v23
	s_nop 0
	v_cndmask_b32_e64 v24, v23, v24, s[48:49]
	v_fma_f32 v23, -v25, v23, v22
	v_cmp_lt_f32_e64 s[48:49], 0, v23
	s_nop 1
	v_cndmask_b32_e64 v23, v24, v25, s[48:49]
	v_mul_f32_e32 v24, 0x37800000, v23
	v_cndmask_b32_e32 v23, v23, v24, vcc
	v_cmp_class_f32_e32 vcc, v22, v215
	s_nop 1
	v_cndmask_b32_e32 v22, v23, v22, vcc
	v_div_scale_f32 v23, s[4:5], v22, v22, 1.0
	v_rcp_f32_e32 v24, v23
	s_nop 0
	v_fma_f32 v25, -v23, v24, 1.0
	v_fmac_f32_e32 v24, v25, v24
	v_div_scale_f32 v25, vcc, 1.0, v22, 1.0
	v_mul_f32_e32 v65, v25, v24
	v_fma_f32 v74, -v23, v65, v25
	v_fmac_f32_e32 v65, v74, v24
	v_fma_f32 v23, -v23, v65, v25
	v_div_fmas_f32 v23, v23, v24, v65
	v_div_fixup_f32 v22, v23, v22, 1.0
	v_pk_mul_f32 v[24:25], v[18:19], v[22:23] op_sel_hi:[1,0]
	v_pk_mul_f32 v[74:75], v[20:21], v[22:23] op_sel_hi:[1,0]
	v_pk_mul_f32 v[18:19], v[24:25], v[104:105]
	v_pk_mul_f32 v[20:21], v[74:75], v[106:107]
	v_cvt_pk_bf16_f32 v24, v18, v19
	v_lshl_add_u64 v[18:19], s[54:55], 0, v[46:47]
	v_cvt_pk_bf16_f32 v25, v20, v21
	v_add_co_u32_e32 v20, vcc, 0x18600000, v18
	s_nop 1
	v_addc_co_u32_e32 v21, vcc, 0, v19, vcc
	global_store_dwordx2 v[20:21], v[24:25], off
	s_and_saveexec_b64 s[48:49], s[40:41]
	s_cbranch_execz .LBB0_557
	v_mov_b32_e32 v23, v22
	v_mov_b32_e32 v20, v22
	v_mov_b32_e32 v21, v22
	v_pk_mul_f32 v[20:21], v[16:17], v[20:21]
	v_pk_mul_f32 v[22:23], v[14:15], v[22:23]
	v_pk_mul_f32 v[16:17], v[20:21], v[110:111]
	v_pk_mul_f32 v[14:15], v[22:23], v[108:109]
	s_nop 0
	v_cvt_pk_bf16_f32 v14, v14, v15
	v_cvt_pk_bf16_f32 v15, v16, v17
	v_add_co_u32_e32 v16, vcc, 0x18600000, v18
	s_nop 1
	v_addc_co_u32_e32 v17, vcc, 0, v19, vcc
	global_store_dwordx2 v[16:17], v[14:15], off offset:512
	s_or_b64 exec, exec, s[48:49]
	s_and_saveexec_b64 s[4:5], s[42:43]
	s_xor_b64 s[48:49], exec, s[4:5]
	s_cbranch_execnz .LBB0_558

; DI unsigned short f2bf(float f) { return (unsigned short)(cvtpk(f, 0.f) & 0xffffu); }
; __global__ void __launch_bounds__(NTHR, 2) mega_fwd(Params P) {
;     ...
;                     if (lane < 16) {
;                         const float2 cs = tabM[(size_t)pos * 16 + lane];
;                         const float o1 = x1[k] * cs.x - x2[k] * cs.y, o2 = x2[k] * cs.x + x1[k] * cs.y;
;                         okr[lane] = o1; okr[16 + lane] = o2;
;                         KR[kvr * 32 + lane] = f2bf(o1); KR[kvr * 32 + 16 + lane] = f2bf(o2);
.LBB0_556:
	v_lshl_add_u64 v[14:15], s[52:53], 0, v[72:73]
	v_lshlrev_b64 v[16:17], 7, v[70:71]
	v_lshl_add_u64 v[14:15], v[14:15], 0, v[16:17]
	v_and_b32_e32 v16, 0x1fff, v26
	v_or_b32_e32 v17, 0x1000, v59
	v_cndmask_b32_e64 v16, v17, v16, s[46:47]
	v_lshl_or_b32 v16, v16, 7, v32
	v_mov_b32_e32 v16, v116
	v_mov_b32_e32 v17, v117
	v_mul_f32_e32 v18, v60, v17
	v_mul_f32_e32 v19, v62, v17
	v_fma_f32 v18, v62, v16, -v18
	v_fmac_f32_e32 v19, v60, v16
	v_lshlrev_b32_e32 v16, 2, v28
	v_mov_b32_e32 v17, v0
	v_lshl_add_u64 v[14:15], v[14:15], 0, v[16:17]
	global_store_dword v[14:15], v18, off nt
	global_store_dword v[14:15], v19, off offset:64 nt
	v_lshlrev_b64 v[14:15], 6, v[68:69]
	v_cvt_pk_bf16_f32 v16, v18, s0
	v_lshl_add_u64 v[14:15], v[40:41], 0, v[14:15]
	global_store_short v[14:15], v16, off
	v_cvt_pk_bf16_f32 v16, v19, s0
	global_store_short v[14:15], v16, off offset:32
	s_or_b64 exec, exec, s[48:49]
	s_and_saveexec_b64 s[48:49], s[44:45]
	s_cbranch_execz .LBB0_530
	s_branch .LBB0_562

; DI unsigned cvtpk(float lo, float hi) { f32x2_t v = {lo, hi}; bf16x2_t b = __builtin_convertvector(v, bf16x2_t); return __builtin_bit_cast(unsigned, b); }
; __global__ void __launch_bounds__(NTHR, 2) mega_fwd(Params P) {
;     ...
;                 for (int k = 0; k < 2; ++k) {
;                     if (k == 1 && !has1) break;
;                     const int m = mm[k]; const int pos = pos_of_row(m); const size_t kvr = (size_t)kvrow_of_row(m);
;                     float* ockv; float* okr;
;                     if (m < MP) { ockv = outp + O_CKVP + ((size_t)ll * MP + m) * 256; okr = outp + O_KRP + ((size_t)ll * MP + m) * 32; }
;                     else { ockv = outp + O_CKVS + ((size_t)ll * MS + (m - MP)) * 256; okr = outp + O_KRS + ((size_t)ll * MS + (m - MP)) * 32; }
;                     {
;                         const float rs = 1.f / sqrtf(sk[k] * (1.f / 256.f) + EPS);
;                         const f32x4 o = vk[k] * rs * ((const f32x4*)gkv)[lane];
;                         ((f32x4*)ockv)[lane] = o;
;                         u32x2 w; w.x = cvtpk(o.x, o.y); w.y = cvtpk(o.z, o.w); ((u32x2*)(CKVB + kvr * 256))[lane] = w;
;                     }
;                     {
;                         const float rs = 1.f / sqrtf(sq[k] * (1.f / 384.f) + EPS);
;                         const f32x4 o0 = vq0[k] * rs * ((const f32x4*)gq)[lane];
;                         u32x2 w; w.x = cvtpk(o0.x, o0.y); w.y = cvtpk(o0.z, o0.w); ((u32x2*)(CQ + (size_t)m * 384))[lane] = w;
;                         if (lane < 32) { const f32x4 o1 = vq1[k] * rs * ((const f32x4*)(gq + 256))[lane]; u32x2 w1; w1.x = cvtpk(o1.x, o1.y); w1.y = cvtpk(o1.z, o1.w); ((u32x2*)(CQ + (size_t)m * 384 + 256))[lane] = w1; }
;                     }
.LBB0_562:
	v_ashrrev_i32_e32 v59, 31, v58
	s_mov_b32 s4, 0x8000
	v_cmp_gt_i32_e64 s[44:45], s4, v56
	v_cmp_lt_i32_e32 vcc, s9, v56
	v_and_b32_e32 v22, 63, v56
	v_add_u32_e32 v18, 0xffff8000, v56
	v_mov_b64_e32 v[14:15], v[58:59]
	s_and_saveexec_b64 s[46:47], vcc
	v_lshrrev_b32_e32 v14, 6, v18
	s_movk_i32 s4, 0x1040
	v_mul_lo_u32 v14, v14, s4
	v_or_b32_e32 v14, v14, v22
	v_add_u32_e32 v14, 0x9000, v14
	v_mov_b32_e32 v15, v0
	s_or_b64 exec, exec, s[46:47]
	s_and_saveexec_b64 s[4:5], vcc
	s_xor_b64 s[46:47], exec, s[4:5]
	v_mov_b32_e32 v19, v0
	v_lshl_add_u64 v[16:17], s[58:59], 0, v[18:19]
	s_or_saveexec_b64 s[46:47], s[46:47]
	v_mov_b64_e32 v[18:19], 0xd000000
	v_mov_b64_e32 v[20:21], 0xcf00000
	s_xor_b64 exec, exec, s[46:47]
	v_lshl_add_u64 v[16:17], s[60:61], 0, v[58:59]
	v_mov_b64_e32 v[18:19], 0xc200000
	v_mov_b64_e32 v[20:21], 0x8200000
	s_or_b64 exec, exec, s[46:47]
	s_waitcnt lgkmcnt(1)
	v_add_f32_e32 v23, v33, v67
	v_lshl_add_u64 v[20:21], s[52:53], 0, v[20:21]
	v_lshlrev_b64 v[24:25], 10, v[16:17]
	v_fmamk_f32 v23, v23, 0x3b800000, v214
	v_lshl_add_u64 v[20:21], v[20:21], 0, v[24:25]
	v_cmp_gt_f32_e32 vcc, s6, v23
	v_mul_f32_e32 v24, 0x4f800000, v23
	s_waitcnt lgkmcnt(0)
	v_add_f32_e32 v33, v57, v81
	v_cndmask_b32_e32 v23, v23, v24, vcc
	v_sqrt_f32_e32 v24, v23
	v_mov_b32_e32 v65, v0
	v_lshl_add_u64 v[20:21], v[20:21], 0, v[64:65]
	v_add_u32_e32 v25, -1, v24
	v_fma_f32 v57, -v25, v24, v23
	v_cmp_ge_f32_e64 s[46:47], 0, v57
	v_add_u32_e32 v57, 1, v24
	s_nop 0
	v_cndmask_b32_e64 v25, v24, v25, s[46:47]
	v_fma_f32 v24, -v57, v24, v23
	v_cmp_lt_f32_e64 s[46:47], 0, v24
	s_nop 1
	v_cndmask_b32_e64 v24, v25, v57, s[46:47]
	v_mul_f32_e32 v25, 0x37800000, v24
	v_cndmask_b32_e32 v24, v24, v25, vcc
	v_cmp_class_f32_e32 vcc, v23, v215
	s_nop 1
	v_cndmask_b32_e32 v23, v24, v23, vcc
	v_div_scale_f32 v24, s[4:5], v23, v23, 1.0
	v_rcp_f32_e32 v25, v24
	s_nop 0
	v_fma_f32 v57, -v24, v25, 1.0
	v_fmac_f32_e32 v25, v57, v25
	v_div_scale_f32 v57, vcc, 1.0, v23, 1.0
	v_mul_f32_e32 v60, v57, v25
	v_fma_f32 v62, -v24, v60, v57
	v_fmac_f32_e32 v60, v62, v25
	v_fma_f32 v24, -v24, v60, v57
	v_div_fmas_f32 v24, v24, v25, v60
	v_div_fixup_f32 v24, v24, v23, 1.0
	v_pk_mul_f32 v[66:67], v[10:11], v[24:25] op_sel_hi:[1,0]
	v_pk_mul_f32 v[24:25], v[12:13], v[24:25] op_sel_hi:[1,0]
	v_pk_mul_f32 v[12:13], v[24:25], v[102:103]
	v_pk_mul_f32 v[10:11], v[66:67], v[100:101]
	global_store_dwordx4 v[20:21], v[10:13], off nt
	s_nop 1
	v_cvt_pk_bf16_f32 v10, v10, v11
	v_cvt_pk_bf16_f32 v11, v12, v13
	v_lshlrev_b64 v[12:13], 9, v[14:15]
	v_lshl_add_u64 v[12:13], v[34:35], 0, v[12:13]
	global_store_dwordx2 v[12:13], v[10:11], off
	v_fmamk_f32 v10, v33, 0x3b2aaaab, v214
	v_cmp_gt_f32_e32 vcc, s6, v10
	v_mul_f32_e32 v11, 0x4f800000, v10
	s_nop 0
	v_cndmask_b32_e32 v10, v10, v11, vcc
	v_sqrt_f32_e32 v11, v10
	s_nop 0
	v_add_u32_e32 v12, -1, v11
	v_fma_f32 v13, -v12, v11, v10
	v_cmp_ge_f32_e64 s[46:47], 0, v13
	v_add_u32_e32 v13, 1, v11
	s_nop 0
	v_cndmask_b32_e64 v12, v11, v12, s[46:47]
	v_fma_f32 v11, -v13, v11, v10
	v_cmp_lt_f32_e64 s[46:47], 0, v11
	s_nop 1
	v_cndmask_b32_e64 v11, v12, v13, s[46:47]
	v_mul_f32_e32 v12, 0x37800000, v11
	v_cndmask_b32_e32 v11, v11, v12, vcc
	v_cmp_class_f32_e32 vcc, v10, v215
	s_nop 1
	v_cndmask_b32_e32 v10, v11, v10, vcc
	v_div_scale_f32 v11, s[4:5], v10, v10, 1.0
	v_rcp_f32_e32 v12, v11
	s_movk_i32 s4, 0x300
	v_fma_f32 v13, -v11, v12, 1.0
	v_fmac_f32_e32 v12, v13, v12
	v_div_scale_f32 v13, vcc, 1.0, v10, 1.0
	v_mul_f32_e32 v20, v13, v12
	v_fma_f32 v21, -v11, v20, v13
	v_fmac_f32_e32 v20, v21, v12
	v_fma_f32 v11, -v11, v20, v13
	v_div_fmas_f32 v11, v11, v12, v20
	v_div_fixup_f32 v10, v11, v10, 1.0
	v_pk_mul_f32 v[6:7], v[6:7], v[10:11] op_sel_hi:[1,0]
	v_pk_mul_f32 v[8:9], v[8:9], v[10:11] op_sel_hi:[1,0]
	v_pk_mul_f32 v[6:7], v[6:7], v[104:105]
	v_pk_mul_f32 v[8:9], v[8:9], v[106:107]
	v_cvt_pk_bf16_f32 v12, v6, v7
	v_cvt_pk_bf16_f32 v13, v8, v9
	v_mad_i64_i32 v[6:7], s[4:5], v58, s4, v[44:45]
	global_store_dwordx2 v[6:7], v[12:13], off
	s_and_saveexec_b64 s[46:47], s[40:41]
	s_cbranch_execz .LBB0_571
	v_mov_b32_e32 v11, v10
	v_mov_b32_e32 v8, v10
	v_mov_b32_e32 v9, v10
	v_pk_mul_f32 v[8:9], v[4:5], v[8:9]
	v_pk_mul_f32 v[10:11], v[2:3], v[10:11]
	v_pk_mul_f32 v[4:5], v[8:9], v[110:111]
	v_pk_mul_f32 v[2:3], v[10:11], v[108:109]
	s_nop 0
	v_cvt_pk_bf16_f32 v2, v2, v3
	v_cvt_pk_bf16_f32 v3, v4, v5
	global_store_dwordx2 v[6:7], v[2:3], off offset:512
	s_or_b64 exec, exec, s[46:47]
	s_and_saveexec_b64 s[4:5], s[42:43]
	s_xor_b64 s[46:47], exec, s[4:5]
	s_cbranch_execnz .LBB0_572

; DI unsigned short f2bf(float f) { return (unsigned short)(cvtpk(f, 0.f) & 0xffffu); }
; __global__ void __launch_bounds__(NTHR, 2) mega_fwd(Params P) {
;     ...
;                     if (lane < 16) {
;                         const float2 cs = tabM[(size_t)pos * 16 + lane];
;                         const float o1 = x1[k] * cs.x - x2[k] * cs.y, o2 = x2[k] * cs.x + x1[k] * cs.y;
;                         okr[lane] = o1; okr[16 + lane] = o2;
;                         KR[kvr * 32 + lane] = f2bf(o1); KR[kvr * 32 + 16 + lane] = f2bf(o2);
.LBB0_575:
	v_lshl_add_u64 v[2:3], s[52:53], 0, v[18:19]
	v_lshlrev_b64 v[4:5], 7, v[16:17]
	v_lshl_add_u64 v[2:3], v[2:3], 0, v[4:5]
	v_and_b32_e32 v1, 0x1fff, v56
	v_or_b32_e32 v4, 0x1000, v22
	v_cndmask_b32_e64 v1, v4, v1, s[44:45]
	v_lshl_or_b32 v1, v1, 7, v32
	v_mov_b32_e32 v4, v118
	v_mov_b32_e32 v5, v119
	v_mul_f32_e32 v1, v63, v5
	v_mul_f32_e32 v6, v61, v5
	v_fma_f32 v1, v61, v4, -v1
	v_fmac_f32_e32 v6, v63, v4
	v_lshlrev_b32_e32 v4, 2, v28
	v_mov_b32_e32 v5, v0
	v_lshl_add_u64 v[2:3], v[2:3], 0, v[4:5]
	global_store_dword v[2:3], v1, off nt
	global_store_dword v[2:3], v6, off offset:64 nt
	v_lshlrev_b64 v[2:3], 6, v[14:15]
	v_cvt_pk_bf16_f32 v1, v1, s0
	v_lshl_add_u64 v[2:3], v[40:41], 0, v[2:3]
	global_store_short v[2:3], v1, off
	v_cvt_pk_bf16_f32 v1, v6, s0
	global_store_short v[2:3], v1, off offset:32
	s_branch .LBB0_530
